# v023 + exposed xor-32 ds_bpermute shuffles in attention bodies replaced by v_mov + v_permlane32_swap (9 sites)
# baseline (speedup 1.0000x reference)
; template <int MODE, class Src>
; DI void attn_item(LAS unsigned char* lds, const Src& src, const bf16_t* Qp  , bf16_t* Op  , int nband, int jj0, float sink_l2, const LAS float* tbl, int qbase, int tid) {
;     ...
;         float bm = fmaxf(s[0][0], s[1][0]);
; #pragma unroll
;         for (int i = 1; i < 16; ++i) bm = fmaxf(bm, fmaxf(s[0][i], s[1][i]));
;         bm = bm * esc + bc;
;         bm = fmaxf(bm, __shfl_xor(bm, 32));
;         if (__builtin_amdgcn_ballot_w64(bm > mrun + 8.0f) != 0ull) {
;             const float mnew = fmaxf(mrun, bm), alpha = __builtin_amdgcn_exp2f(mrun - mnew);
;             lrun *= alpha; mrun = mnew;
; #pragma unroll
;             for (int db = 0; db < 4; ++db)
; #pragma unroll
;                 for (int i = 0; i < 16; ++i) o[db][i] *= alpha;
;         }
.LBB0_491:
	s_nop 10
	v_max_f32_e32 v139, v85, v85
	v_max_f32_e32 v145, v69, v69
	v_max_f32_e32 v139, v145, v139
	v_max_f32_e32 v145, v86, v86
	v_max_f32_e32 v161, v70, v70
	v_max_f32_e32 v145, v161, v145
	v_max_f32_e32 v161, v87, v87
	v_max_f32_e32 v162, v71, v71
	v_max3_f32 v139, v68, v84, v139
	v_max_f32_e32 v161, v162, v161
	v_max3_f32 v139, v139, v145, v161
	v_max_f32_e32 v145, v88, v88
	v_max_f32_e32 v161, v72, v72
	v_max_f32_e32 v145, v161, v145
	v_max_f32_e32 v161, v89, v89
	v_max_f32_e32 v162, v73, v73
	v_max_f32_e32 v161, v162, v161
	v_max3_f32 v139, v139, v145, v161
	v_max_f32_e32 v145, v90, v90
	v_max_f32_e32 v161, v74, v74
	v_max_f32_e32 v145, v161, v145
	v_max_f32_e32 v161, v91, v91
	v_max_f32_e32 v162, v75, v75
	v_max_f32_e32 v161, v162, v161
	v_max3_f32 v139, v139, v145, v161
	v_max_f32_e32 v145, v92, v92
	v_max_f32_e32 v161, v76, v76
	v_max_f32_e32 v145, v161, v145
	v_max_f32_e32 v161, v93, v93
	v_max_f32_e32 v162, v77, v77
	v_max_f32_e32 v161, v162, v161
	v_max3_f32 v139, v139, v145, v161
	v_max_f32_e32 v145, v94, v94
	v_max_f32_e32 v161, v78, v78
	v_max_f32_e32 v145, v161, v145
	v_max_f32_e32 v161, v95, v95
	v_max_f32_e32 v162, v79, v79
	v_max_f32_e32 v161, v162, v161
	v_max3_f32 v139, v139, v145, v161
	v_max_f32_e32 v145, v96, v96
	v_max_f32_e32 v161, v80, v80
	v_max_f32_e32 v145, v161, v145
	v_max_f32_e32 v161, v97, v97
	v_max_f32_e32 v162, v81, v81
	v_max_f32_e32 v161, v162, v161
	v_max3_f32 v139, v139, v145, v161
	v_max_f32_e32 v145, v98, v98
	v_max_f32_e32 v161, v82, v82
	v_max_f32_e32 v145, v161, v145
	v_max_f32_e32 v161, v99, v99
	v_max_f32_e32 v162, v83, v83
	v_max_f32_e32 v161, v162, v161
	v_max3_f32 v139, v139, v145, v161
	v_and_b32_e32 v161, 64, v223
	v_fma_f32 v145, v139, s30, 0
	v_xor_b32_e32 v139, 32, v223
	v_add_u32_e32 v161, 64, v161
	v_cmp_lt_i32_e32 vcc, v139, v161
	s_nop 1
	v_cndmask_b32_e32 v139, v223, v139, vcc
	v_lshlrev_b32_e32 v139, 2, v139
	v_mov_b32_e32 v161, v145
	s_nop 1
	v_permlane32_swap_b32_e32 v145, v161
	s_waitcnt lgkmcnt(0)
	v_max_f32_e32 v161, v161, v161
	v_max_f32_e32 v145, v145, v161
	v_add_f32_e32 v161, 0x41000000, v137
	v_cmp_gt_f32_e32 vcc, v145, v161
	s_cbranch_vccz .LBB0_493
	v_max_f32_e32 v145, v145, v145
	v_max_f32_e32 v161, v137, v137
	v_max_f32_e32 v145, v161, v145
	v_sub_f32_e32 v137, v137, v145
	v_exp_f32_e32 v162, v137
	v_mov_b32_e32 v137, v145
	v_pk_mul_f32 v[66:67], v[66:67], v[162:163] op_sel_hi:[1,0]
	v_pk_mul_f32 v[64:65], v[64:65], v[162:163] op_sel_hi:[1,0]
	v_pk_mul_f32 v[62:63], v[62:63], v[162:163] op_sel_hi:[1,0]
	v_pk_mul_f32 v[60:61], v[60:61], v[162:163] op_sel_hi:[1,0]
	v_pk_mul_f32 v[58:59], v[58:59], v[162:163] op_sel_hi:[1,0]
	v_pk_mul_f32 v[56:57], v[56:57], v[162:163] op_sel_hi:[1,0]
	v_pk_mul_f32 v[54:55], v[54:55], v[162:163] op_sel_hi:[1,0]
	v_pk_mul_f32 v[52:53], v[52:53], v[162:163] op_sel_hi:[1,0]
	v_pk_mul_f32 v[50:51], v[50:51], v[162:163] op_sel_hi:[1,0]
	v_pk_mul_f32 v[48:49], v[48:49], v[162:163] op_sel_hi:[1,0]
	v_pk_mul_f32 v[46:47], v[46:47], v[162:163] op_sel_hi:[1,0]
	v_pk_mul_f32 v[44:45], v[44:45], v[162:163] op_sel_hi:[1,0]
	v_pk_mul_f32 v[42:43], v[42:43], v[162:163] op_sel_hi:[1,0]
	v_pk_mul_f32 v[40:41], v[40:41], v[162:163] op_sel_hi:[1,0]
	v_pk_mul_f32 v[38:39], v[38:39], v[162:163] op_sel_hi:[1,0]
	v_pk_mul_f32 v[36:37], v[36:37], v[162:163] op_sel_hi:[1,0]
	v_pk_mul_f32 v[34:35], v[34:35], v[162:163] op_sel_hi:[1,0]
	v_pk_mul_f32 v[32:33], v[32:33], v[162:163] op_sel_hi:[1,0]
	v_pk_mul_f32 v[30:31], v[30:31], v[162:163] op_sel_hi:[1,0]
	v_pk_mul_f32 v[28:29], v[28:29], v[162:163] op_sel_hi:[1,0]
	v_pk_mul_f32 v[26:27], v[26:27], v[162:163] op_sel_hi:[1,0]
	v_pk_mul_f32 v[24:25], v[24:25], v[162:163] op_sel_hi:[1,0]
	v_pk_mul_f32 v[22:23], v[22:23], v[162:163] op_sel_hi:[1,0]
	v_pk_mul_f32 v[20:21], v[20:21], v[162:163] op_sel_hi:[1,0]
	v_pk_mul_f32 v[18:19], v[18:19], v[162:163] op_sel_hi:[1,0]
	v_pk_mul_f32 v[16:17], v[16:17], v[162:163] op_sel_hi:[1,0]
	v_pk_mul_f32 v[14:15], v[14:15], v[162:163] op_sel_hi:[1,0]
	v_pk_mul_f32 v[12:13], v[12:13], v[162:163] op_sel_hi:[1,0]
	v_pk_mul_f32 v[10:11], v[10:11], v[162:163] op_sel_hi:[1,0]
	v_pk_mul_f32 v[8:9], v[8:9], v[162:163] op_sel_hi:[1,0]
	v_pk_mul_f32 v[6:7], v[6:7], v[162:163] op_sel_hi:[1,0]
	v_pk_mul_f32 v[4:5], v[4:5], v[162:163] op_sel_hi:[1,0]
	v_mul_f32_e32 v135, v135, v162

; #define LAS __attribute__((address_space(3)))
; DI unsigned pk2(float a, float b) { f32x2 v = {a, b}; bf16v2 r = __builtin_convertvector(v, bf16v2); return __builtin_bit_cast(unsigned, r); }
; #define MFMA32(a, b, cc) __builtin_amdgcn_mfma_f32_32x32x16_bf16((a), (b), (cc), 0, 0, 0)
; DI void attn_quad(LAS unsigned char* lds, const bf16_t* Z, bf16_t* BR, int c0  , int head, const LAS float* tbl, int tid) {
;     ...
;         float ps = 0.f; const float eoff = bc - mrun;
; #pragma unroll
;         for (int kb = 0; kb < 2; ++kb)
; #pragma unroll
;             for (int i = 0; i < 16; ++i) { s[kb][i] = __builtin_amdgcn_exp2f(__builtin_fmaf(s[kb][i], esc, eoff)); ps += s[kb][i]; }
;         ps += __shfl_xor(ps, 32);
;         lrun += ps;
; #pragma unroll
;         for (int kb = 0; kb < 2; ++kb)
; #pragma unroll
;             for (int st = 0; st < 2; ++st) {
;                 u32x4 pp; pp.x = pk2(s[kb][8 * st + 0], s[kb][8 * st + 1]); pp.y = pk2(s[kb][8 * st + 2], s[kb][8 * st + 3]); pp.z = pk2(s[kb][8 * st + 4], s[kb][8 * st + 5]); pp.w = pk2(s[kb][8 * st + 6], s[kb][8 * st + 7]);
;                 const bf16x8 pf = __builtin_bit_cast(bf16x8, pp);
; #pragma unroll
;                 for (int db = 0; db < 4; ++db) {
;                     s16x4 v2[2];
; #pragma unroll
;                     for (int t = 0; t < 2; ++t) {
;                         const int f = (q << 2) | ((2 * t + h) & 3);
;                         v2[t] = __builtin_amdgcn_ds_read_tr16_b64_v4i16((LAS s16x4*)(Vt + 256 * (32 * kb + 16 * st + 8 * t) + 16 * ((4 * db + vlo) ^ f)));
;                     }
;                     const bf16x8 vf = __builtin_shufflevector(v2[0], v2[1], 0, 1, 2, 3, 4, 5, 6, 7);
;                     o[db] = MFMA32(vf, pf, o[db]);
;                 }
;             }
.LBB0_561:
	v_sub_f32_e32 v100, v100, v149
	v_fma_f32 v68, s23, v68, v100
	v_exp_f32_e32 v101, v68
	v_fma_f32 v69, s23, v69, v100
	v_exp_f32_e32 v102, v69
	v_fma_f32 v69, s23, v70, v100
	v_exp_f32_e32 v103, v69
	v_fma_f32 v69, s23, v71, v100
	v_exp_f32_e32 v104, v69
	v_fma_f32 v69, s23, v72, v100
	v_add_f32_e32 v68, 0, v101
	v_exp_f32_e32 v105, v69
	v_fma_f32 v69, s23, v73, v100
	v_add_f32_e32 v68, v102, v68
	v_exp_f32_e32 v106, v69
	v_fma_f32 v69, s23, v74, v100
	v_add_f32_e32 v68, v103, v68
	v_exp_f32_e32 v107, v69
	v_fma_f32 v69, s23, v75, v100
	v_add_f32_e32 v68, v104, v68
	v_exp_f32_e32 v108, v69
	v_fma_f32 v69, s23, v76, v100
	v_add_f32_e32 v68, v105, v68
	v_exp_f32_e32 v109, v69
	v_fma_f32 v69, s23, v77, v100
	v_add_f32_e32 v68, v106, v68
	v_exp_f32_e32 v110, v69
	v_fma_f32 v69, s23, v78, v100
	v_add_f32_e32 v68, v107, v68
	v_exp_f32_e32 v111, v69
	v_fma_f32 v69, s23, v79, v100
	v_add_f32_e32 v68, v108, v68
	v_exp_f32_e32 v112, v69
	v_fma_f32 v69, s23, v80, v100
	v_add_f32_e32 v68, v109, v68
	v_exp_f32_e32 v113, v69
	v_fma_f32 v69, s23, v81, v100
	v_add_f32_e32 v68, v110, v68
	v_exp_f32_e32 v114, v69
	v_fma_f32 v69, s23, v82, v100
	v_add_f32_e32 v68, v111, v68
	v_exp_f32_e32 v82, v69
	v_fma_f32 v69, s23, v83, v100
	v_add_f32_e32 v68, v112, v68
	v_exp_f32_e32 v83, v69
	v_fma_f32 v69, s23, v84, v100
	v_add_f32_e32 v68, v113, v68
	v_exp_f32_e32 v84, v69
	v_fma_f32 v69, s23, v85, v100
	v_add_f32_e32 v68, v114, v68
	v_exp_f32_e32 v85, v69
	v_fma_f32 v69, s23, v86, v100
	v_add_f32_e32 v68, v82, v68
	v_exp_f32_e32 v86, v69
	v_fma_f32 v69, s23, v87, v100
	v_add_f32_e32 v68, v83, v68
	v_exp_f32_e32 v87, v69
	v_fma_f32 v69, s23, v88, v100
	v_add_f32_e32 v68, v84, v68
	v_exp_f32_e32 v88, v69
	v_fma_f32 v69, s23, v89, v100
	v_add_f32_e32 v68, v85, v68
	v_exp_f32_e32 v89, v69
	v_fma_f32 v69, s23, v90, v100
	v_add_f32_e32 v68, v86, v68
	v_exp_f32_e32 v90, v69
	v_fma_f32 v69, s23, v91, v100
	v_add_f32_e32 v68, v87, v68
	v_exp_f32_e32 v91, v69
	v_add_f32_e32 v68, v88, v68
	v_add_f32_e32 v68, v89, v68
	v_add_f32_e32 v68, v90, v68
	v_add_f32_e32 v69, v91, v68
	v_fma_f32 v68, s23, v92, v100
	v_exp_f32_e32 v68, v68
	v_fma_f32 v75, s23, v98, v100
	v_exp_f32_e32 v92, v75
	v_cvt_pk_bf16_f32 v75, v103, v104
	v_add_f32_e32 v70, v68, v69
	v_fma_f32 v69, s23, v93, v100
	v_exp_f32_e32 v69, v69
	v_cvt_pk_bf16_f32 v76, v105, v106
	v_cvt_pk_bf16_f32 v77, v107, v108
	v_add_u32_e32 v98, v141, v174
	v_add_f32_e32 v71, v69, v70
	v_fma_f32 v70, s23, v94, v100
	v_exp_f32_e32 v70, v70
	v_add_u32_e32 v94, v141, v170
	s_waitcnt vmcnt(0)
	v_cvt_pk_bf16_f32 v68, v68, v69
	v_add_f32_e32 v72, v70, v71
	v_fma_f32 v71, s23, v95, v100
	v_exp_f32_e32 v71, v71
	v_add_u32_e32 v95, v141, v171
	ds_read_b64_tr_b16 v[116:117], v94
	ds_read_b64_tr_b16 v[118:119], v95 offset:2048
	v_add_f32_e32 v73, v71, v72
	v_fma_f32 v72, s23, v96, v100
	v_exp_f32_e32 v72, v72
	v_add_u32_e32 v96, v141, v172
	v_cvt_pk_bf16_f32 v69, v70, v71
	v_add_f32_e32 v74, v72, v73
	v_fma_f32 v73, s23, v97, v100
	v_exp_f32_e32 v73, v73
	v_fmac_f32_e32 v100, s23, v99
	v_exp_f32_e32 v93, v100
	v_add_u32_e32 v97, v141, v173
	ds_read_b64_tr_b16 v[120:121], v96
	ds_read_b64_tr_b16 v[122:123], v97 offset:2048
	v_add_f32_e32 v74, v73, v74
	v_add_f32_e32 v74, v92, v74
	v_add_f32_e32 v74, v93, v74
	v_mov_b32_e32 v2, v74
	s_nop 1
	v_permlane32_swap_b32_e32 v74, v2
	s_waitcnt lgkmcnt(0)
	v_add_u32_e32 v99, v141, v175
	ds_read_b64_tr_b16 v[132:133], v98
	ds_read_b64_tr_b16 v[134:135], v99 offset:2048
	v_add_u32_e32 v100, v141, v169
	v_cvt_pk_bf16_f32 v70, v72, v73
	v_cvt_pk_bf16_f32 v71, v92, v93
	v_add_f32_e32 v2, v74, v2
	v_cvt_pk_bf16_f32 v74, v101, v102
	v_add_u32_e32 v101, v141, v176
	ds_read_b64_tr_b16 v[152:153], v100
	ds_read_b64_tr_b16 v[154:155], v101 offset:2048
	ds_read_b64_tr_b16 v[156:157], v94 offset:4096
	ds_read_b64_tr_b16 v[158:159], v95 offset:6144
	ds_read_b64_tr_b16 v[186:187], v96 offset:4096
	ds_read_b64_tr_b16 v[188:189], v97 offset:6144
	ds_read_b64_tr_b16 v[190:191], v98 offset:4096
	ds_read_b64_tr_b16 v[192:193], v99 offset:6144
	v_add_f32_e32 v145, v145, v2
	s_waitcnt lgkmcnt(12)
	v_mfma_f32_32x32x16_bf16 v[52:67], v[116:119], v[74:77], v[52:67]
	ds_read_b64_tr_b16 v[204:205], v100 offset:4096
	ds_read_b64_tr_b16 v[206:207], v101 offset:6144
	s_waitcnt lgkmcnt(12)
	v_mfma_f32_32x32x16_bf16 v[36:51], v[120:123], v[74:77], v[36:51]
	ds_read_b64_tr_b16 v[116:117], v94 offset:8192
	ds_read_b64_tr_b16 v[118:119], v95 offset:10240
	s_waitcnt lgkmcnt(12)
	v_mfma_f32_32x32x16_bf16 v[20:35], v[132:135], v[74:77], v[20:35]
	ds_read_b64_tr_b16 v[120:121], v96 offset:8192
	ds_read_b64_tr_b16 v[122:123], v97 offset:10240
	s_waitcnt lgkmcnt(12)
	v_mfma_f32_32x32x16_bf16 v[4:19], v[152:155], v[74:77], v[4:19]
	ds_read_b64_tr_b16 v[132:133], v98 offset:8192
	ds_read_b64_tr_b16 v[134:135], v99 offset:10240
	v_cvt_pk_bf16_f32 v74, v109, v110
	v_cvt_pk_bf16_f32 v75, v111, v112
	v_cvt_pk_bf16_f32 v76, v113, v114
	v_cvt_pk_bf16_f32 v77, v82, v83
	s_nop 0
	s_waitcnt lgkmcnt(12)
	v_mfma_f32_32x32x16_bf16 v[52:67], v[156:159], v[74:77], v[52:67]
	ds_read_b64_tr_b16 v[152:153], v100 offset:8192
	ds_read_b64_tr_b16 v[154:155], v101 offset:10240
	s_waitcnt lgkmcnt(12)
	v_mfma_f32_32x32x16_bf16 v[36:51], v[186:189], v[74:77], v[36:51]
	ds_read_b64_tr_b16 v[156:157], v94 offset:12288
	ds_read_b64_tr_b16 v[158:159], v95 offset:14336
	s_waitcnt lgkmcnt(12)
	v_mfma_f32_32x32x16_bf16 v[20:35], v[190:193], v[74:77], v[20:35]
	ds_read_b64_tr_b16 v[186:187], v96 offset:12288
	ds_read_b64_tr_b16 v[188:189], v97 offset:14336
	s_waitcnt lgkmcnt(12)
	v_mfma_f32_32x32x16_bf16 v[4:19], v[204:207], v[74:77], v[4:19]
	ds_read_b64_tr_b16 v[190:191], v98 offset:12288
	ds_read_b64_tr_b16 v[192:193], v99 offset:14336
	v_cvt_pk_bf16_f32 v74, v84, v85
	v_cvt_pk_bf16_f32 v75, v86, v87
	v_cvt_pk_bf16_f32 v76, v88, v89
	v_cvt_pk_bf16_f32 v77, v90, v91
	s_nop 0
	s_waitcnt lgkmcnt(12)
	v_mfma_f32_32x32x16_bf16 v[52:67], v[116:119], v[74:77], v[52:67]
	ds_read_b64_tr_b16 v[204:205], v100 offset:12288
	ds_read_b64_tr_b16 v[206:207], v101 offset:14336
	s_waitcnt lgkmcnt(12)
	v_mfma_f32_32x32x16_bf16 v[36:51], v[120:123], v[74:77], v[36:51]
	s_waitcnt lgkmcnt(10)
	v_mfma_f32_32x32x16_bf16 v[20:35], v[132:135], v[74:77], v[20:35]
	s_waitcnt lgkmcnt(8)
	v_mfma_f32_32x32x16_bf16 v[4:19], v[152:155], v[74:77], v[4:19]
	s_waitcnt lgkmcnt(6)
	v_mfma_f32_32x32x16_bf16 v[52:67], v[156:159], v[68:71], v[52:67]
	s_waitcnt lgkmcnt(4)
	v_mfma_f32_32x32x16_bf16 v[36:51], v[186:189], v[68:71], v[36:51]
	s_waitcnt lgkmcnt(2)
	v_mfma_f32_32x32x16_bf16 v[20:35], v[190:193], v[68:71], v[20:35]
	s_waitcnt lgkmcnt(0)
	v_mfma_f32_32x32x16_bf16 v[4:19], v[204:207], v[68:71], v[4:19]

; #define LAS __attribute__((address_space(3)))
; DI unsigned pk2(float a, float b) { f32x2 v = {a, b}; bf16v2 r = __builtin_convertvector(v, bf16v2); return __builtin_bit_cast(unsigned, r); }
; #define MFMA32(a, b, cc) __builtin_amdgcn_mfma_f32_32x32x16_bf16((a), (b), (cc), 0, 0, 0)
; DI void attn_quad(LAS unsigned char* lds, const bf16_t* Z, bf16_t* BR, int c0  , int head, const LAS float* tbl, int tid) {
;     ...
;         float ps = 0.f; const float eoff = bc - mrun;
; #pragma unroll
;         for (int kb = 0; kb < 2; ++kb)
; #pragma unroll
;             for (int i = 0; i < 16; ++i) { s[kb][i] = __builtin_amdgcn_exp2f(__builtin_fmaf(s[kb][i], esc, eoff)); ps += s[kb][i]; }
;         ps += __shfl_xor(ps, 32);
;         lrun += ps;
; #pragma unroll
;         for (int kb = 0; kb < 2; ++kb)
; #pragma unroll
;             for (int st = 0; st < 2; ++st) {
;                 u32x4 pp; pp.x = pk2(s[kb][8 * st + 0], s[kb][8 * st + 1]); pp.y = pk2(s[kb][8 * st + 2], s[kb][8 * st + 3]); pp.z = pk2(s[kb][8 * st + 4], s[kb][8 * st + 5]); pp.w = pk2(s[kb][8 * st + 6], s[kb][8 * st + 7]);
;                 const bf16x8 pf = __builtin_bit_cast(bf16x8, pp);
; #pragma unroll
;                 for (int db = 0; db < 4; ++db) {
;                     s16x4 v2[2];
; #pragma unroll
;                     for (int t = 0; t < 2; ++t) {
;                         const int f = (q << 2) | ((2 * t + h) & 3);
;                         v2[t] = __builtin_amdgcn_ds_read_tr16_b64_v4i16((LAS s16x4*)(Vt + 256 * (32 * kb + 16 * st + 8 * t) + 16 * ((4 * db + vlo) ^ f)));
;                     }
;                     const bf16x8 vf = __builtin_shufflevector(v2[0], v2[1], 0, 1, 2, 3, 4, 5, 6, 7);
;                     o[db] = MFMA32(vf, pf, o[db]);
;                 }
;             }
.LBB0_564:
	v_sub_f32_e32 v137, v137, v149
	v_fma_f32 v68, s48, v68, v137
	v_exp_f32_e32 v154, v68
	v_fma_f32 v69, s48, v69, v137
	v_exp_f32_e32 v155, v69
	v_fma_f32 v69, s48, v70, v137
	v_exp_f32_e32 v156, v69
	v_fma_f32 v69, s48, v71, v137
	v_exp_f32_e32 v157, v69
	v_fma_f32 v69, s48, v72, v137
	v_add_f32_e32 v68, 0, v154
	v_exp_f32_e32 v158, v69
	v_fma_f32 v69, s48, v73, v137
	v_add_f32_e32 v68, v155, v68
	v_exp_f32_e32 v159, v69
	v_fma_f32 v69, s48, v74, v137
	v_add_f32_e32 v68, v156, v68
	v_exp_f32_e32 v74, v69
	v_fma_f32 v69, s48, v75, v137
	v_add_f32_e32 v68, v157, v68
	v_exp_f32_e32 v75, v69
	v_fma_f32 v69, s48, v76, v137
	v_add_f32_e32 v68, v158, v68
	v_exp_f32_e32 v184, v69
	v_fma_f32 v69, s48, v77, v137
	v_add_f32_e32 v68, v159, v68
	v_exp_f32_e32 v77, v69
	v_fma_f32 v69, s48, v78, v137
	v_add_f32_e32 v68, v74, v68
	v_exp_f32_e32 v185, v69
	v_fma_f32 v69, s48, v79, v137
	v_add_f32_e32 v68, v75, v68
	v_exp_f32_e32 v186, v69
	v_fma_f32 v69, s48, v80, v137
	v_add_f32_e32 v68, v184, v68
	v_exp_f32_e32 v187, v69
	v_fma_f32 v69, s48, v81, v137
	v_add_f32_e32 v68, v77, v68
	v_exp_f32_e32 v188, v69
	v_fma_f32 v69, s48, v82, v137
	v_add_f32_e32 v68, v185, v68
	v_exp_f32_e32 v189, v69
	v_fma_f32 v69, s48, v83, v137
	v_add_f32_e32 v68, v186, v68
	v_exp_f32_e32 v190, v69
	v_fma_f32 v69, s48, v84, v137
	v_add_f32_e32 v68, v187, v68
	v_exp_f32_e32 v191, v69
	v_fma_f32 v69, s48, v85, v137
	v_add_f32_e32 v68, v188, v68
	v_exp_f32_e32 v192, v69
	v_fma_f32 v69, s48, v86, v137
	v_add_f32_e32 v68, v189, v68
	v_exp_f32_e32 v86, v69
	v_fma_f32 v69, s48, v87, v137
	v_add_f32_e32 v68, v190, v68
	v_exp_f32_e32 v87, v69
	v_fma_f32 v69, s48, v88, v137
	v_add_f32_e32 v68, v191, v68
	v_exp_f32_e32 v88, v69
	v_fma_f32 v69, s48, v89, v137
	v_add_f32_e32 v68, v192, v68
	v_exp_f32_e32 v89, v69
	v_fma_f32 v69, s48, v90, v137
	v_add_f32_e32 v68, v86, v68
	v_exp_f32_e32 v90, v69
	v_fma_f32 v69, s48, v91, v137
	v_add_f32_e32 v68, v87, v68
	v_exp_f32_e32 v91, v69
	v_add_f32_e32 v68, v88, v68
	v_add_f32_e32 v68, v89, v68
	v_add_f32_e32 v68, v90, v68
	v_add_f32_e32 v69, v91, v68
	v_fma_f32 v68, s48, v92, v137
	v_exp_f32_e32 v68, v68
	v_fma_f32 v78, s48, v98, v137
	v_exp_f32_e32 v92, v78
	v_add3_u32 v153, s47, v183, v179
	v_add_f32_e32 v70, v68, v69
	v_fma_f32 v69, s48, v93, v137
	v_exp_f32_e32 v69, v69
	v_cvt_pk_bf16_f32 v81, v74, v75
	v_add_u32_e32 v74, v153, v170
	v_add_u32_e32 v75, v153, v171
	v_add_f32_e32 v71, v69, v70
	v_fma_f32 v70, s48, v94, v137
	v_exp_f32_e32 v70, v70
	s_waitcnt vmcnt(0)
	ds_read_b64_tr_b16 v[204:205], v74 offset:16384
	ds_read_b64_tr_b16 v[206:207], v75 offset:18432
	v_cvt_pk_bf16_f32 v79, v156, v157
	v_add_f32_e32 v72, v70, v71
	v_fma_f32 v71, s48, v95, v137
	v_exp_f32_e32 v71, v71
	v_cvt_pk_bf16_f32 v80, v158, v159
	v_add_u32_e32 v94, v153, v172
	v_add_u32_e32 v95, v153, v173
	ds_read_b64_tr_b16 v[208:209], v94 offset:16384
	ds_read_b64_tr_b16 v[210:211], v95 offset:18432
	v_add_f32_e32 v73, v71, v72
	v_fma_f32 v72, s48, v96, v137
	v_exp_f32_e32 v72, v72
	v_add_u32_e32 v96, v153, v174
	v_add_u32_e32 v98, v153, v169
	v_cvt_pk_bf16_f32 v68, v68, v69
	v_add_f32_e32 v76, v72, v73
	v_fma_f32 v73, s48, v97, v137
	v_exp_f32_e32 v73, v73
	v_fmac_f32_e32 v137, s48, v99
	v_exp_f32_e32 v93, v137
	v_add_u32_e32 v97, v153, v175
	ds_read_b64_tr_b16 v[212:213], v96 offset:16384
	ds_read_b64_tr_b16 v[214:215], v97 offset:18432
	v_add_f32_e32 v76, v73, v76
	v_add_f32_e32 v76, v92, v76
	v_add_f32_e32 v76, v93, v76
	v_mov_b32_e32 v78, v76
	s_nop 1
	v_permlane32_swap_b32_e32 v76, v78
	s_waitcnt lgkmcnt(0)
	v_add_u32_e32 v99, v153, v176
	ds_read_b64_tr_b16 v[230:231], v98 offset:16384
	ds_read_b64_tr_b16 v[232:233], v99 offset:18432
	ds_read_b64_tr_b16 v[234:235], v74 offset:20480
	ds_read_b64_tr_b16 v[236:237], v75 offset:22528
	ds_read_b64_tr_b16 v[238:239], v94 offset:20480
	ds_read_b64_tr_b16 v[240:241], v95 offset:22528
	ds_read_b64_tr_b16 v[242:243], v96 offset:20480
	ds_read_b64_tr_b16 v[244:245], v97 offset:22528
	v_cvt_pk_bf16_f32 v69, v70, v71
	v_cvt_pk_bf16_f32 v70, v72, v73
	v_cvt_pk_bf16_f32 v71, v92, v93
	v_add_f32_e32 v76, v76, v78
	v_cvt_pk_bf16_f32 v78, v154, v155
	v_add_f32_e32 v145, v145, v76
	s_nop 0
	s_waitcnt lgkmcnt(12)
	v_mfma_f32_32x32x16_bf16 v[52:67], v[204:207], v[78:81], v[52:67]
	ds_read_b64_tr_b16 v[246:247], v98 offset:20480
	ds_read_b64_tr_b16 v[248:249], v99 offset:22528
	s_waitcnt lgkmcnt(12)
	v_mfma_f32_32x32x16_bf16 v[36:51], v[208:211], v[78:81], v[36:51]
	ds_read_b64_tr_b16 v[204:205], v74 offset:24576
	ds_read_b64_tr_b16 v[206:207], v75 offset:26624
	s_waitcnt lgkmcnt(12)
	v_mfma_f32_32x32x16_bf16 v[20:35], v[212:215], v[78:81], v[20:35]
	ds_read_b64_tr_b16 v[208:209], v94 offset:24576
	ds_read_b64_tr_b16 v[210:211], v95 offset:26624
	s_waitcnt lgkmcnt(12)
	v_mfma_f32_32x32x16_bf16 v[4:19], v[230:233], v[78:81], v[4:19]
	ds_read_b64_tr_b16 v[212:213], v96 offset:24576
	ds_read_b64_tr_b16 v[214:215], v97 offset:26624
	v_cvt_pk_bf16_f32 v78, v184, v77
	v_cvt_pk_bf16_f32 v79, v185, v186
	v_cvt_pk_bf16_f32 v80, v187, v188
	v_cvt_pk_bf16_f32 v81, v189, v190
	s_nop 0
	s_waitcnt lgkmcnt(12)
	v_mfma_f32_32x32x16_bf16 v[52:67], v[234:237], v[78:81], v[52:67]
	ds_read_b64_tr_b16 v[230:231], v74 offset:28672
	ds_read_b64_tr_b16 v[232:233], v75 offset:30720
	s_waitcnt lgkmcnt(12)
	v_mfma_f32_32x32x16_bf16 v[36:51], v[238:241], v[78:81], v[36:51]
	ds_read_b64_tr_b16 v[234:235], v94 offset:28672
	ds_read_b64_tr_b16 v[236:237], v95 offset:30720
	s_waitcnt lgkmcnt(12)
	v_mfma_f32_32x32x16_bf16 v[20:35], v[242:245], v[78:81], v[20:35]
	ds_read_b64_tr_b16 v[238:239], v98 offset:24576
	ds_read_b64_tr_b16 v[240:241], v99 offset:26624
	s_waitcnt lgkmcnt(12)
	v_mfma_f32_32x32x16_bf16 v[4:19], v[246:249], v[78:81], v[4:19]
	ds_read_b64_tr_b16 v[242:243], v96 offset:28672
	ds_read_b64_tr_b16 v[244:245], v97 offset:30720
	v_cvt_pk_bf16_f32 v78, v191, v192
	v_cvt_pk_bf16_f32 v79, v86, v87
	v_cvt_pk_bf16_f32 v80, v88, v89
	v_cvt_pk_bf16_f32 v81, v90, v91
	s_nop 0
	s_waitcnt lgkmcnt(12)
	v_mfma_f32_32x32x16_bf16 v[52:67], v[204:207], v[78:81], v[52:67]
	ds_read_b64_tr_b16 v[246:247], v98 offset:28672
	ds_read_b64_tr_b16 v[248:249], v99 offset:30720
	s_waitcnt lgkmcnt(12)
	v_mfma_f32_32x32x16_bf16 v[36:51], v[208:211], v[78:81], v[36:51]
	s_waitcnt lgkmcnt(10)
	v_mfma_f32_32x32x16_bf16 v[20:35], v[212:215], v[78:81], v[20:35]
	s_waitcnt lgkmcnt(8)
	v_mfma_f32_32x32x16_bf16 v[52:67], v[230:233], v[68:71], v[52:67]
	s_waitcnt lgkmcnt(6)
	v_mfma_f32_32x32x16_bf16 v[36:51], v[234:237], v[68:71], v[36:51]
	s_waitcnt lgkmcnt(4)
	v_mfma_f32_32x32x16_bf16 v[4:19], v[238:241], v[78:81], v[4:19]
	s_waitcnt lgkmcnt(2)
	v_mfma_f32_32x32x16_bf16 v[20:35], v[242:245], v[68:71], v[20:35]
	s_waitcnt lgkmcnt(0)
	v_mfma_f32_32x32x16_bf16 v[4:19], v[246:249], v[68:71], v[4:19]

; DI void attn_quad(LAS unsigned char* lds, const bf16_t* Z, bf16_t* BR, int c0  , int head, const LAS float* tbl, int tid) {
;     ...
;         float bm = fmaxf(s[0][0], s[1][0]);
; #pragma unroll
;         for (int i = 1; i < 16; ++i) bm = fmaxf(bm, fmaxf(s[0][i], s[1][i]));
;         bm = bm * esc + bc;
;         bm = fmaxf(bm, __shfl_xor(bm, 32));
;         if (__builtin_amdgcn_ballot_w64(bm > mrun + 8.0f) != 0ull) {
;             const float mnew = fmaxf(mrun, bm), alpha = __builtin_amdgcn_exp2f(mrun - mnew);
;             lrun *= alpha; mrun = mnew;
; #pragma unroll
;             for (int db = 0; db < 4; ++db)
; #pragma unroll
;                 for (int i = 0; i < 16; ++i) o[db][i] *= alpha;
;         }
.LBB0_577:
	s_nop 6
	v_max_f32_e32 v152, v85, v85
	v_max_f32_e32 v153, v69, v69
	v_max_f32_e32 v152, v153, v152
	v_max_f32_e32 v153, v86, v86
	v_max_f32_e32 v154, v70, v70
	v_max_f32_e32 v153, v154, v153
	v_max_f32_e32 v154, v87, v87
	v_max_f32_e32 v155, v71, v71
	v_max3_f32 v152, v68, v84, v152
	v_max_f32_e32 v154, v155, v154
	v_max3_f32 v152, v152, v153, v154
	v_max_f32_e32 v153, v88, v88
	v_max_f32_e32 v154, v72, v72
	v_max_f32_e32 v153, v154, v153
	v_max_f32_e32 v154, v89, v89
	v_max_f32_e32 v155, v73, v73
	v_max_f32_e32 v154, v155, v154
	v_max3_f32 v152, v152, v153, v154
	v_max_f32_e32 v153, v90, v90
	v_max_f32_e32 v154, v74, v74
	v_max_f32_e32 v153, v154, v153
	v_max_f32_e32 v154, v91, v91
	v_max_f32_e32 v155, v75, v75
	v_max_f32_e32 v154, v155, v154
	v_max3_f32 v152, v152, v153, v154
	v_max_f32_e32 v153, v92, v92
	v_max_f32_e32 v154, v76, v76
	v_max_f32_e32 v153, v154, v153
	v_max_f32_e32 v154, v93, v93
	v_max_f32_e32 v155, v77, v77
	v_max_f32_e32 v154, v155, v154
	v_max3_f32 v152, v152, v153, v154
	v_max_f32_e32 v153, v94, v94
	v_max_f32_e32 v154, v78, v78
	v_max_f32_e32 v153, v154, v153
	v_max_f32_e32 v154, v95, v95
	v_max_f32_e32 v155, v79, v79
	v_max_f32_e32 v154, v155, v154
	v_max3_f32 v152, v152, v153, v154
	v_max_f32_e32 v153, v96, v96
	v_max_f32_e32 v154, v80, v80
	v_max_f32_e32 v153, v154, v153
	v_max_f32_e32 v154, v97, v97
	v_max_f32_e32 v155, v81, v81
	v_max_f32_e32 v154, v155, v154
	v_max3_f32 v152, v152, v153, v154
	v_max_f32_e32 v153, v98, v98
	v_max_f32_e32 v154, v82, v82
	v_max_f32_e32 v153, v154, v153
	v_max_f32_e32 v154, v99, v99
	v_max_f32_e32 v155, v83, v83
	v_max_f32_e32 v154, v155, v154
	v_max3_f32 v152, v152, v153, v154
	v_and_b32_e32 v154, 64, v223
	s_waitcnt lgkmcnt(0)
	v_fma_f32 v153, s48, v152, v137
	v_xor_b32_e32 v152, 32, v223
	v_add_u32_e32 v154, 64, v154
	v_cmp_lt_i32_e32 vcc, v152, v154
	s_nop 1
	v_cndmask_b32_e32 v152, v223, v152, vcc
	v_lshlrev_b32_e32 v152, 2, v152
	v_mov_b32_e32 v154, v153
	s_nop 1
	v_permlane32_swap_b32_e32 v153, v154
	s_waitcnt lgkmcnt(0)
	v_max_f32_e32 v154, v154, v154
	v_max_f32_e32 v153, v153, v154
	v_add_f32_e32 v154, 0x41000000, v149
	v_cmp_gt_f32_e32 vcc, v153, v154
	s_cbranch_vccz .LBB0_564
	v_max_f32_e32 v153, v153, v153
	v_max_f32_e32 v154, v149, v149
	v_max_f32_e32 v153, v154, v153
	v_sub_f32_e32 v149, v149, v153
	v_exp_f32_e32 v154, v149
	v_mov_b32_e32 v149, v153
	v_pk_mul_f32 v[66:67], v[66:67], v[154:155] op_sel_hi:[1,0]
	v_pk_mul_f32 v[64:65], v[64:65], v[154:155] op_sel_hi:[1,0]
	v_pk_mul_f32 v[62:63], v[62:63], v[154:155] op_sel_hi:[1,0]
	v_pk_mul_f32 v[60:61], v[60:61], v[154:155] op_sel_hi:[1,0]
	v_pk_mul_f32 v[58:59], v[58:59], v[154:155] op_sel_hi:[1,0]
	v_pk_mul_f32 v[56:57], v[56:57], v[154:155] op_sel_hi:[1,0]
	v_pk_mul_f32 v[54:55], v[54:55], v[154:155] op_sel_hi:[1,0]
	v_pk_mul_f32 v[52:53], v[52:53], v[154:155] op_sel_hi:[1,0]
	v_pk_mul_f32 v[50:51], v[50:51], v[154:155] op_sel_hi:[1,0]
	v_pk_mul_f32 v[48:49], v[48:49], v[154:155] op_sel_hi:[1,0]
	v_pk_mul_f32 v[46:47], v[46:47], v[154:155] op_sel_hi:[1,0]
	v_pk_mul_f32 v[44:45], v[44:45], v[154:155] op_sel_hi:[1,0]
	v_pk_mul_f32 v[42:43], v[42:43], v[154:155] op_sel_hi:[1,0]
	v_pk_mul_f32 v[40:41], v[40:41], v[154:155] op_sel_hi:[1,0]
	v_pk_mul_f32 v[38:39], v[38:39], v[154:155] op_sel_hi:[1,0]
	v_pk_mul_f32 v[36:37], v[36:37], v[154:155] op_sel_hi:[1,0]
	v_pk_mul_f32 v[34:35], v[34:35], v[154:155] op_sel_hi:[1,0]
	v_pk_mul_f32 v[32:33], v[32:33], v[154:155] op_sel_hi:[1,0]
	v_pk_mul_f32 v[30:31], v[30:31], v[154:155] op_sel_hi:[1,0]
	v_pk_mul_f32 v[28:29], v[28:29], v[154:155] op_sel_hi:[1,0]
	v_pk_mul_f32 v[26:27], v[26:27], v[154:155] op_sel_hi:[1,0]
	v_pk_mul_f32 v[24:25], v[24:25], v[154:155] op_sel_hi:[1,0]
	v_pk_mul_f32 v[22:23], v[22:23], v[154:155] op_sel_hi:[1,0]
	v_pk_mul_f32 v[20:21], v[20:21], v[154:155] op_sel_hi:[1,0]
	v_pk_mul_f32 v[18:19], v[18:19], v[154:155] op_sel_hi:[1,0]
	v_pk_mul_f32 v[16:17], v[16:17], v[154:155] op_sel_hi:[1,0]
	v_pk_mul_f32 v[14:15], v[14:15], v[154:155] op_sel_hi:[1,0]
	v_pk_mul_f32 v[12:13], v[12:13], v[154:155] op_sel_hi:[1,0]
	v_pk_mul_f32 v[10:11], v[10:11], v[154:155] op_sel_hi:[1,0]
	v_pk_mul_f32 v[8:9], v[8:9], v[154:155] op_sel_hi:[1,0]
	v_pk_mul_f32 v[6:7], v[6:7], v[154:155] op_sel_hi:[1,0]
	v_pk_mul_f32 v[4:5], v[4:5], v[154:155] op_sel_hi:[1,0]
	v_mul_f32_e32 v145, v145, v154
	s_branch .LBB0_564

; DI void attn_quad(LAS unsigned char* lds, const bf16_t* Z, bf16_t* BR, int c0  , int head, const LAS float* tbl, int tid) {
;     ...
;         float bm = fmaxf(s[0][0], s[1][0]);
; #pragma unroll
;         for (int i = 1; i < 16; ++i) bm = fmaxf(bm, fmaxf(s[0][i], s[1][i]));
;         bm = bm * esc + bc;
;         bm = fmaxf(bm, __shfl_xor(bm, 32));
;         if (__builtin_amdgcn_ballot_w64(bm > mrun + 8.0f) != 0ull) {
;             const float mnew = fmaxf(mrun, bm), alpha = __builtin_amdgcn_exp2f(mrun - mnew);
;             lrun *= alpha; mrun = mnew;
; #pragma unroll
;             for (int db = 0; db < 4; ++db)
; #pragma unroll
;                 for (int i = 0; i < 16; ++i) o[db][i] *= alpha;
;         }
.LBB0_584:
	s_nop 6
	v_max_f32_e32 v208, v85, v85
	v_max_f32_e32 v209, v69, v69
	v_max_f32_e32 v208, v209, v208
	v_max_f32_e32 v209, v86, v86
	v_max_f32_e32 v210, v70, v70
	v_max_f32_e32 v209, v210, v209
	v_max_f32_e32 v210, v87, v87
	v_max_f32_e32 v211, v71, v71
	v_max3_f32 v208, v68, v84, v208
	v_max_f32_e32 v210, v211, v210
	v_max3_f32 v208, v208, v209, v210
	v_max_f32_e32 v209, v88, v88
	v_max_f32_e32 v210, v72, v72
	v_max_f32_e32 v209, v210, v209
	v_max_f32_e32 v210, v89, v89
	v_max_f32_e32 v211, v73, v73
	v_max_f32_e32 v210, v211, v210
	v_max3_f32 v208, v208, v209, v210
	v_max_f32_e32 v209, v90, v90
	v_max_f32_e32 v210, v74, v74
	v_max_f32_e32 v209, v210, v209
	v_max_f32_e32 v210, v91, v91
	v_max_f32_e32 v211, v75, v75
	v_max_f32_e32 v210, v211, v210
	v_max3_f32 v208, v208, v209, v210
	v_max_f32_e32 v209, v92, v92
	v_max_f32_e32 v210, v76, v76
	v_max_f32_e32 v209, v210, v209
	v_max_f32_e32 v210, v93, v93
	v_max_f32_e32 v211, v77, v77
	v_max_f32_e32 v210, v211, v210
	v_max3_f32 v208, v208, v209, v210
	v_max_f32_e32 v209, v94, v94
	v_max_f32_e32 v210, v78, v78
	v_max_f32_e32 v209, v210, v209
	v_max_f32_e32 v210, v95, v95
	v_max_f32_e32 v211, v79, v79
	v_max_f32_e32 v210, v211, v210
	v_max3_f32 v208, v208, v209, v210
	v_max_f32_e32 v209, v96, v96
	v_max_f32_e32 v210, v80, v80
	v_max_f32_e32 v209, v210, v209
	v_max_f32_e32 v210, v97, v97
	v_max_f32_e32 v211, v81, v81
	v_max_f32_e32 v210, v211, v210
	v_max3_f32 v208, v208, v209, v210
	v_max_f32_e32 v209, v98, v98
	v_max_f32_e32 v210, v82, v82
	v_max_f32_e32 v209, v210, v209
	v_max_f32_e32 v210, v99, v99
	v_max_f32_e32 v211, v83, v83
	v_max_f32_e32 v210, v211, v210
	v_max3_f32 v208, v208, v209, v210
	v_and_b32_e32 v210, 64, v223
	s_waitcnt lgkmcnt(0)
	v_fma_f32 v209, s26, v208, v207
	v_xor_b32_e32 v208, 32, v223
	v_add_u32_e32 v210, 64, v210
	v_cmp_lt_i32_e32 vcc, v208, v210
	s_nop 1
	v_cndmask_b32_e32 v208, v223, v208, vcc
	v_lshlrev_b32_e32 v208, 2, v208
	v_mov_b32_e32 v210, v209
	s_nop 1
	v_permlane32_swap_b32_e32 v209, v210
	s_waitcnt lgkmcnt(0)
	v_max_f32_e32 v210, v210, v210
	v_max_f32_e32 v209, v209, v210
	v_add_f32_e32 v210, 0x41000000, v149
	v_cmp_gt_f32_e32 vcc, v209, v210
	s_cbranch_vccz .LBB0_586
	v_max_f32_e32 v209, v209, v209
	v_max_f32_e32 v210, v149, v149
	v_max_f32_e32 v209, v210, v209
	v_sub_f32_e32 v149, v149, v209
	v_exp_f32_e32 v210, v149
	v_mov_b32_e32 v149, v209
	v_pk_mul_f32 v[66:67], v[66:67], v[210:211] op_sel_hi:[1,0]
	v_pk_mul_f32 v[64:65], v[64:65], v[210:211] op_sel_hi:[1,0]
	v_pk_mul_f32 v[62:63], v[62:63], v[210:211] op_sel_hi:[1,0]
	v_pk_mul_f32 v[60:61], v[60:61], v[210:211] op_sel_hi:[1,0]
	v_pk_mul_f32 v[58:59], v[58:59], v[210:211] op_sel_hi:[1,0]
	v_pk_mul_f32 v[56:57], v[56:57], v[210:211] op_sel_hi:[1,0]
	v_pk_mul_f32 v[54:55], v[54:55], v[210:211] op_sel_hi:[1,0]
	v_pk_mul_f32 v[52:53], v[52:53], v[210:211] op_sel_hi:[1,0]
	v_pk_mul_f32 v[50:51], v[50:51], v[210:211] op_sel_hi:[1,0]
	v_pk_mul_f32 v[48:49], v[48:49], v[210:211] op_sel_hi:[1,0]
	v_pk_mul_f32 v[46:47], v[46:47], v[210:211] op_sel_hi:[1,0]
	v_pk_mul_f32 v[44:45], v[44:45], v[210:211] op_sel_hi:[1,0]
	v_pk_mul_f32 v[42:43], v[42:43], v[210:211] op_sel_hi:[1,0]
	v_pk_mul_f32 v[40:41], v[40:41], v[210:211] op_sel_hi:[1,0]
	v_pk_mul_f32 v[38:39], v[38:39], v[210:211] op_sel_hi:[1,0]
	v_pk_mul_f32 v[36:37], v[36:37], v[210:211] op_sel_hi:[1,0]
	v_pk_mul_f32 v[34:35], v[34:35], v[210:211] op_sel_hi:[1,0]
	v_pk_mul_f32 v[32:33], v[32:33], v[210:211] op_sel_hi:[1,0]
	v_pk_mul_f32 v[30:31], v[30:31], v[210:211] op_sel_hi:[1,0]
	v_pk_mul_f32 v[28:29], v[28:29], v[210:211] op_sel_hi:[1,0]
	v_pk_mul_f32 v[26:27], v[26:27], v[210:211] op_sel_hi:[1,0]
	v_pk_mul_f32 v[24:25], v[24:25], v[210:211] op_sel_hi:[1,0]
	v_pk_mul_f32 v[22:23], v[22:23], v[210:211] op_sel_hi:[1,0]
	v_pk_mul_f32 v[20:21], v[20:21], v[210:211] op_sel_hi:[1,0]
	v_pk_mul_f32 v[18:19], v[18:19], v[210:211] op_sel_hi:[1,0]
	v_pk_mul_f32 v[16:17], v[16:17], v[210:211] op_sel_hi:[1,0]
	v_pk_mul_f32 v[14:15], v[14:15], v[210:211] op_sel_hi:[1,0]
	v_pk_mul_f32 v[12:13], v[12:13], v[210:211] op_sel_hi:[1,0]
	v_pk_mul_f32 v[10:11], v[10:11], v[210:211] op_sel_hi:[1,0]
	v_pk_mul_f32 v[8:9], v[8:9], v[210:211] op_sel_hi:[1,0]
	v_pk_mul_f32 v[6:7], v[6:7], v[210:211] op_sel_hi:[1,0]
	v_pk_mul_f32 v[4:5], v[4:5], v[210:211] op_sel_hi:[1,0]
	v_mul_f32_e32 v145, v145, v210
; #define LAS __attribute__((address_space(3)))
; DI unsigned pk2(float a, float b) { f32x2 v = {a, b}; bf16v2 r = __builtin_convertvector(v, bf16v2); return __builtin_bit_cast(unsigned, r); }
; #define MFMA32(a, b, cc) __builtin_amdgcn_mfma_f32_32x32x16_bf16((a), (b), (cc), 0, 0, 0)
; DI void attn_quad(LAS unsigned char* lds, const bf16_t* Z, bf16_t* BR, int c0  , int head, const LAS float* tbl, int tid) {
;     ...
;         float ps = 0.f; const float eoff = bc - mrun;
; #pragma unroll
;         for (int kb = 0; kb < 2; ++kb)
; #pragma unroll
;             for (int i = 0; i < 16; ++i) { s[kb][i] = __builtin_amdgcn_exp2f(__builtin_fmaf(s[kb][i], esc, eoff)); ps += s[kb][i]; }
;         ps += __shfl_xor(ps, 32);
;         lrun += ps;
; #pragma unroll
;         for (int kb = 0; kb < 2; ++kb)
; #pragma unroll
;             for (int st = 0; st < 2; ++st) {
;                 u32x4 pp; pp.x = pk2(s[kb][8 * st + 0], s[kb][8 * st + 1]); pp.y = pk2(s[kb][8 * st + 2], s[kb][8 * st + 3]); pp.z = pk2(s[kb][8 * st + 4], s[kb][8 * st + 5]); pp.w = pk2(s[kb][8 * st + 6], s[kb][8 * st + 7]);
;                 const bf16x8 pf = __builtin_bit_cast(bf16x8, pp);
; #pragma unroll
;                 for (int db = 0; db < 4; ++db) {
;                     s16x4 v2[2];
; #pragma unroll
;                     for (int t = 0; t < 2; ++t) {
;                         const int f = (q << 2) | ((2 * t + h) & 3);
;                         v2[t] = __builtin_amdgcn_ds_read_tr16_b64_v4i16((LAS s16x4*)(Vt + 256 * (32 * kb + 16 * st + 8 * t) + 16 * ((4 * db + vlo) ^ f)));
;                     }
;                     const bf16x8 vf = __builtin_shufflevector(v2[0], v2[1], 0, 1, 2, 3, 4, 5, 6, 7);
;                     o[db] = MFMA32(vf, pf, o[db]);
;                 }
;             }
.LBB0_586:
	v_sub_f32_e32 v207, v207, v149
	v_fma_f32 v68, s26, v68, v207
	v_exp_f32_e32 v209, v68
	v_fma_f32 v69, s26, v69, v207
	v_exp_f32_e32 v210, v69
	v_fma_f32 v69, s26, v70, v207
	v_exp_f32_e32 v211, v69
	v_fma_f32 v69, s26, v71, v207
	v_exp_f32_e32 v212, v69
	v_fma_f32 v69, s26, v72, v207
	v_add_f32_e32 v68, 0, v209
	v_exp_f32_e32 v213, v69
	v_fma_f32 v69, s26, v73, v207
	v_add_f32_e32 v68, v210, v68
	v_exp_f32_e32 v214, v69
	v_fma_f32 v69, s26, v74, v207
	v_add_f32_e32 v68, v211, v68
	v_exp_f32_e32 v74, v69
	v_fma_f32 v69, s26, v75, v207
	v_add_f32_e32 v68, v212, v68
	v_exp_f32_e32 v75, v69
	v_fma_f32 v69, s26, v76, v207
	v_add_f32_e32 v68, v213, v68
	v_exp_f32_e32 v215, v69
	v_fma_f32 v69, s26, v77, v207
	v_add_f32_e32 v68, v214, v68
	v_exp_f32_e32 v77, v69
	v_fma_f32 v69, s26, v78, v207
	v_add_f32_e32 v68, v74, v68
	v_exp_f32_e32 v216, v69
	v_fma_f32 v69, s26, v79, v207
	v_add_f32_e32 v68, v75, v68
	v_exp_f32_e32 v217, v69
	v_fma_f32 v69, s26, v80, v207
	v_add_f32_e32 v68, v215, v68
	v_exp_f32_e32 v230, v69
	v_fma_f32 v69, s26, v81, v207
	v_add_f32_e32 v68, v77, v68
	v_exp_f32_e32 v231, v69
	v_fma_f32 v69, s26, v82, v207
	v_add_f32_e32 v68, v216, v68
	v_exp_f32_e32 v232, v69
	v_fma_f32 v69, s26, v83, v207
	v_add_f32_e32 v68, v217, v68
	v_exp_f32_e32 v233, v69
	v_fma_f32 v69, s26, v84, v207
	v_add_f32_e32 v68, v230, v68
	v_exp_f32_e32 v234, v69
	v_fma_f32 v69, s26, v85, v207
	v_add_f32_e32 v68, v231, v68
	v_exp_f32_e32 v235, v69
	v_fma_f32 v69, s26, v86, v207
	v_add_f32_e32 v68, v232, v68
	v_exp_f32_e32 v86, v69
	v_fma_f32 v69, s26, v87, v207
	v_add_f32_e32 v68, v233, v68
	v_exp_f32_e32 v87, v69
	v_fma_f32 v69, s26, v88, v207
	v_add_f32_e32 v68, v234, v68
	v_exp_f32_e32 v88, v69
	v_fma_f32 v69, s26, v89, v207
	v_add_f32_e32 v68, v235, v68
	v_exp_f32_e32 v89, v69
	v_fma_f32 v69, s26, v90, v207
	v_add_f32_e32 v68, v86, v68
	v_exp_f32_e32 v90, v69
	v_fma_f32 v69, s26, v91, v207
	v_add_f32_e32 v68, v87, v68
	v_exp_f32_e32 v91, v69
	v_add_f32_e32 v68, v88, v68
	v_add_f32_e32 v68, v89, v68
	v_add_f32_e32 v68, v90, v68
	v_add_f32_e32 v69, v91, v68
	v_fma_f32 v68, s26, v92, v207
	v_exp_f32_e32 v68, v68
	v_fma_f32 v78, s26, v98, v207
	v_exp_f32_e32 v92, v78
	v_cvt_pk_bf16_f32 v81, v74, v75
	v_add_f32_e32 v70, v68, v69
	v_fma_f32 v69, s26, v93, v207
	v_exp_f32_e32 v69, v69
	v_add_u32_e32 v74, v143, v170
	v_add_u32_e32 v75, v143, v171
	s_waitcnt vmcnt(0)
	ds_read_b64_tr_b16 v[236:237], v74
	ds_read_b64_tr_b16 v[238:239], v75 offset:2048
	v_add_f32_e32 v71, v69, v70
	v_fma_f32 v70, s26, v94, v207
	v_exp_f32_e32 v70, v70
	v_cvt_pk_bf16_f32 v79, v211, v212
	v_cvt_pk_bf16_f32 v80, v213, v214
	v_add_u32_e32 v94, v143, v172
	v_add_f32_e32 v72, v70, v71
	v_fma_f32 v71, s26, v95, v207
	v_exp_f32_e32 v71, v71
	v_add_u32_e32 v95, v143, v173
	ds_read_b64_tr_b16 v[240:241], v94
	ds_read_b64_tr_b16 v[242:243], v95 offset:2048
	v_add_u32_e32 v98, v143, v169
	v_cvt_pk_bf16_f32 v68, v68, v69
	v_add_f32_e32 v73, v71, v72
	v_fma_f32 v72, s26, v96, v207
	v_exp_f32_e32 v72, v72
	v_add_u32_e32 v96, v143, v174
	v_cvt_pk_bf16_f32 v69, v70, v71
	v_add_f32_e32 v76, v72, v73
	v_fma_f32 v73, s26, v97, v207
	v_exp_f32_e32 v73, v73
	v_fmac_f32_e32 v207, s26, v99
	v_exp_f32_e32 v93, v207
	v_add_u32_e32 v97, v143, v175
	ds_read_b64_tr_b16 v[244:245], v96
	ds_read_b64_tr_b16 v[246:247], v97 offset:2048
	v_add_f32_e32 v76, v73, v76
	v_add_f32_e32 v76, v92, v76
	v_add_f32_e32 v76, v93, v76
	v_mov_b32_e32 v78, v76
	s_nop 1
	v_permlane32_swap_b32_e32 v76, v78
	s_waitcnt lgkmcnt(0)
	v_add_u32_e32 v99, v143, v176
	ds_read_b64_tr_b16 v[248:249], v98
	ds_read_b64_tr_b16 v[250:251], v99 offset:2048
	v_cvt_pk_bf16_f32 v70, v72, v73
	v_cvt_pk_bf16_f32 v71, v92, v93
	v_add_f32_e32 v76, v76, v78
	v_cvt_pk_bf16_f32 v78, v209, v210
	v_add_f32_e32 v145, v145, v76
	s_nop 0
	s_waitcnt lgkmcnt(6)
	v_mfma_f32_32x32x16_bf16 v[52:67], v[236:239], v[78:81], v[52:67]
	ds_read_b64_tr_b16 v[236:237], v74 offset:4096
	ds_read_b64_tr_b16 v[238:239], v75 offset:6144
	s_waitcnt lgkmcnt(6)
	v_mfma_f32_32x32x16_bf16 v[36:51], v[240:243], v[78:81], v[36:51]
	ds_read_b64_tr_b16 v[240:241], v94 offset:4096
	ds_read_b64_tr_b16 v[242:243], v95 offset:6144
	s_waitcnt lgkmcnt(6)
	v_mfma_f32_32x32x16_bf16 v[20:35], v[244:247], v[78:81], v[20:35]
	ds_read_b64_tr_b16 v[244:245], v96 offset:4096
	ds_read_b64_tr_b16 v[246:247], v97 offset:6144
	s_waitcnt lgkmcnt(6)
	v_mfma_f32_32x32x16_bf16 v[4:19], v[248:251], v[78:81], v[4:19]
	ds_read_b64_tr_b16 v[248:249], v98 offset:4096
	ds_read_b64_tr_b16 v[250:251], v99 offset:6144
	v_cvt_pk_bf16_f32 v78, v215, v77
	v_cvt_pk_bf16_f32 v79, v216, v217
	v_cvt_pk_bf16_f32 v80, v230, v231
	v_cvt_pk_bf16_f32 v81, v232, v233
	s_nop 0
	s_waitcnt lgkmcnt(6)
	v_mfma_f32_32x32x16_bf16 v[52:67], v[236:239], v[78:81], v[52:67]
	ds_read_b64_tr_b16 v[236:237], v74 offset:8192
	ds_read_b64_tr_b16 v[238:239], v75 offset:10240
	s_waitcnt lgkmcnt(6)
	v_mfma_f32_32x32x16_bf16 v[36:51], v[240:243], v[78:81], v[36:51]
	ds_read_b64_tr_b16 v[240:241], v94 offset:8192
	ds_read_b64_tr_b16 v[242:243], v95 offset:10240
	s_waitcnt lgkmcnt(6)
	v_mfma_f32_32x32x16_bf16 v[20:35], v[244:247], v[78:81], v[20:35]
	ds_read_b64_tr_b16 v[244:245], v96 offset:8192
	ds_read_b64_tr_b16 v[246:247], v97 offset:10240
	s_waitcnt lgkmcnt(6)
	v_mfma_f32_32x32x16_bf16 v[4:19], v[248:251], v[78:81], v[4:19]
	ds_read_b64_tr_b16 v[248:249], v74 offset:12288
	ds_read_b64_tr_b16 v[250:251], v75 offset:14336
	v_cvt_pk_bf16_f32 v78, v234, v235
	v_cvt_pk_bf16_f32 v79, v86, v87
	v_cvt_pk_bf16_f32 v80, v88, v89
	v_cvt_pk_bf16_f32 v81, v90, v91
	s_nop 0
	s_waitcnt lgkmcnt(6)
	v_mfma_f32_32x32x16_bf16 v[52:67], v[236:239], v[78:81], v[52:67]
	ds_read_b64_tr_b16 v[236:237], v94 offset:12288
	ds_read_b64_tr_b16 v[238:239], v95 offset:14336
	s_waitcnt lgkmcnt(6)
	v_mfma_f32_32x32x16_bf16 v[36:51], v[240:243], v[78:81], v[36:51]
	ds_read_b64_tr_b16 v[240:241], v98 offset:8192
	ds_read_b64_tr_b16 v[242:243], v99 offset:10240
	s_waitcnt lgkmcnt(6)
	v_mfma_f32_32x32x16_bf16 v[20:35], v[244:247], v[78:81], v[20:35]
	ds_read_b64_tr_b16 v[244:245], v96 offset:12288
	ds_read_b64_tr_b16 v[246:247], v97 offset:14336
	s_waitcnt lgkmcnt(6)
	v_mfma_f32_32x32x16_bf16 v[52:67], v[248:251], v[68:71], v[52:67]
	ds_read_b64_tr_b16 v[248:249], v98 offset:12288
	ds_read_b64_tr_b16 v[250:251], v99 offset:14336
	s_waitcnt lgkmcnt(6)
	v_mfma_f32_32x32x16_bf16 v[36:51], v[236:239], v[68:71], v[36:51]
	s_waitcnt lgkmcnt(4)
	v_mfma_f32_32x32x16_bf16 v[4:19], v[240:243], v[78:81], v[4:19]
	s_waitcnt lgkmcnt(2)
	v_mfma_f32_32x32x16_bf16 v[20:35], v[244:247], v[68:71], v[20:35]
	s_waitcnt lgkmcnt(0)
	v_mfma_f32_32x32x16_bf16 v[4:19], v[248:251], v[68:71], v[4:19]

; DI void attn_quad(LAS unsigned char* lds, const bf16_t* Z, bf16_t* BR, int c0  , int head, const LAS float* tbl, int tid) {
;     ...
;         float bm = fmaxf(s[0][0], s[1][0]);
; #pragma unroll
;         for (int i = 1; i < 16; ++i) bm = fmaxf(bm, fmaxf(s[0][i], s[1][i]));
;         bm = bm * esc + bc;
;         bm = fmaxf(bm, __shfl_xor(bm, 32));
;         if (__builtin_amdgcn_ballot_w64(bm > mrun + 8.0f) != 0ull) {
;             const float mnew = fmaxf(mrun, bm), alpha = __builtin_amdgcn_exp2f(mrun - mnew);
;             lrun *= alpha; mrun = mnew;
; #pragma unroll
;             for (int db = 0; db < 4; ++db)
; #pragma unroll
;                 for (int i = 0; i < 16; ++i) o[db][i] *= alpha;
;         }
.LBB0_592:
	s_nop 6
	v_max_f32_e32 v2, v85, v85
	v_max_f32_e32 v101, v69, v69
	v_max_f32_e32 v2, v101, v2
	v_max_f32_e32 v101, v86, v86
	v_max_f32_e32 v102, v70, v70
	v_max_f32_e32 v101, v102, v101
	v_max_f32_e32 v102, v87, v87
	v_max_f32_e32 v103, v71, v71
	v_max3_f32 v2, v68, v84, v2
	v_max_f32_e32 v102, v103, v102
	v_max3_f32 v2, v2, v101, v102
	v_max_f32_e32 v101, v88, v88
	v_max_f32_e32 v102, v72, v72
	v_max_f32_e32 v101, v102, v101
	v_max_f32_e32 v102, v89, v89
	v_max_f32_e32 v103, v73, v73
	v_max_f32_e32 v102, v103, v102
	v_max3_f32 v2, v2, v101, v102
	v_max_f32_e32 v101, v90, v90
	v_max_f32_e32 v102, v74, v74
	v_max_f32_e32 v101, v102, v101
	v_max_f32_e32 v102, v91, v91
	v_max_f32_e32 v103, v75, v75
	v_max_f32_e32 v102, v103, v102
	v_max3_f32 v2, v2, v101, v102
	v_max_f32_e32 v101, v92, v92
	v_max_f32_e32 v102, v76, v76
	v_max_f32_e32 v101, v102, v101
	v_max_f32_e32 v102, v93, v93
	v_max_f32_e32 v103, v77, v77
	v_max_f32_e32 v102, v103, v102
	v_max3_f32 v2, v2, v101, v102
	v_max_f32_e32 v101, v94, v94
	v_max_f32_e32 v102, v78, v78
	v_max_f32_e32 v101, v102, v101
	v_max_f32_e32 v102, v95, v95
	v_max_f32_e32 v103, v79, v79
	v_max_f32_e32 v102, v103, v102
	v_max3_f32 v2, v2, v101, v102
	v_max_f32_e32 v101, v96, v96
	v_max_f32_e32 v102, v80, v80
	v_max_f32_e32 v101, v102, v101
	v_max_f32_e32 v102, v97, v97
	v_max_f32_e32 v103, v81, v81
	v_max_f32_e32 v102, v103, v102
	v_max3_f32 v2, v2, v101, v102
	v_max_f32_e32 v101, v98, v98
	v_max_f32_e32 v102, v82, v82
	v_max_f32_e32 v101, v102, v101
	v_max_f32_e32 v102, v99, v99
	v_max_f32_e32 v103, v83, v83
	v_max_f32_e32 v102, v103, v102
	v_max3_f32 v2, v2, v101, v102
	v_and_b32_e32 v102, 64, v223
	s_waitcnt lgkmcnt(0)
	v_fma_f32 v101, s23, v2, v100
	v_xor_b32_e32 v2, 32, v223
	v_add_u32_e32 v102, 64, v102
	v_cmp_lt_i32_e32 vcc, v2, v102
	s_nop 1
	v_cndmask_b32_e32 v2, v223, v2, vcc
	v_lshlrev_b32_e32 v2, 2, v2
	v_mov_b32_e32 v102, v101
	s_nop 1
	v_permlane32_swap_b32_e32 v101, v102
	s_waitcnt lgkmcnt(0)
	v_max_f32_e32 v102, v102, v102
	v_max_f32_e32 v101, v101, v102
	v_add_f32_e32 v102, 0x41000000, v149
	v_cmp_gt_f32_e32 vcc, v101, v102
	s_cbranch_vccz .LBB0_561
	v_max_f32_e32 v101, v101, v101
	v_max_f32_e32 v102, v149, v149
	v_max_f32_e32 v101, v102, v101
	v_sub_f32_e32 v102, v149, v101
	v_exp_f32_e32 v102, v102
	v_mov_b32_e32 v149, v101
	v_pk_mul_f32 v[66:67], v[66:67], v[102:103] op_sel_hi:[1,0]
	v_pk_mul_f32 v[64:65], v[64:65], v[102:103] op_sel_hi:[1,0]
	v_pk_mul_f32 v[62:63], v[62:63], v[102:103] op_sel_hi:[1,0]
	v_pk_mul_f32 v[60:61], v[60:61], v[102:103] op_sel_hi:[1,0]
	v_pk_mul_f32 v[58:59], v[58:59], v[102:103] op_sel_hi:[1,0]
	v_pk_mul_f32 v[56:57], v[56:57], v[102:103] op_sel_hi:[1,0]
	v_pk_mul_f32 v[54:55], v[54:55], v[102:103] op_sel_hi:[1,0]
	v_pk_mul_f32 v[52:53], v[52:53], v[102:103] op_sel_hi:[1,0]
	v_pk_mul_f32 v[50:51], v[50:51], v[102:103] op_sel_hi:[1,0]
	v_pk_mul_f32 v[48:49], v[48:49], v[102:103] op_sel_hi:[1,0]
	v_pk_mul_f32 v[46:47], v[46:47], v[102:103] op_sel_hi:[1,0]
	v_pk_mul_f32 v[44:45], v[44:45], v[102:103] op_sel_hi:[1,0]
	v_pk_mul_f32 v[42:43], v[42:43], v[102:103] op_sel_hi:[1,0]
	v_pk_mul_f32 v[40:41], v[40:41], v[102:103] op_sel_hi:[1,0]
	v_pk_mul_f32 v[38:39], v[38:39], v[102:103] op_sel_hi:[1,0]
	v_pk_mul_f32 v[36:37], v[36:37], v[102:103] op_sel_hi:[1,0]
	v_pk_mul_f32 v[34:35], v[34:35], v[102:103] op_sel_hi:[1,0]
	v_pk_mul_f32 v[32:33], v[32:33], v[102:103] op_sel_hi:[1,0]
	v_pk_mul_f32 v[30:31], v[30:31], v[102:103] op_sel_hi:[1,0]
	v_pk_mul_f32 v[28:29], v[28:29], v[102:103] op_sel_hi:[1,0]
	v_pk_mul_f32 v[26:27], v[26:27], v[102:103] op_sel_hi:[1,0]
	v_pk_mul_f32 v[24:25], v[24:25], v[102:103] op_sel_hi:[1,0]
	v_pk_mul_f32 v[22:23], v[22:23], v[102:103] op_sel_hi:[1,0]
	v_pk_mul_f32 v[20:21], v[20:21], v[102:103] op_sel_hi:[1,0]
	v_pk_mul_f32 v[18:19], v[18:19], v[102:103] op_sel_hi:[1,0]
	v_pk_mul_f32 v[16:17], v[16:17], v[102:103] op_sel_hi:[1,0]
	v_pk_mul_f32 v[14:15], v[14:15], v[102:103] op_sel_hi:[1,0]
	v_pk_mul_f32 v[12:13], v[12:13], v[102:103] op_sel_hi:[1,0]
	v_pk_mul_f32 v[10:11], v[10:11], v[102:103] op_sel_hi:[1,0]
	v_pk_mul_f32 v[8:9], v[8:9], v[102:103] op_sel_hi:[1,0]
	v_pk_mul_f32 v[6:7], v[6:7], v[102:103] op_sel_hi:[1,0]
	v_pk_mul_f32 v[4:5], v[4:5], v[102:103] op_sel_hi:[1,0]
	v_mul_f32_e32 v145, v145, v102
	s_branch .LBB0_561

; template <int MODE, class Src>
; DI void attn_item(LAS unsigned char* lds, const Src& src, const bf16_t* Qp  , bf16_t* Op  , int nband, int jj0, float sink_l2, const LAS float* tbl, int qbase, int tid) {
;     ...
;         float bm = fmaxf(s[0][0], s[1][0]);
; #pragma unroll
;         for (int i = 1; i < 16; ++i) bm = fmaxf(bm, fmaxf(s[0][i], s[1][i]));
;         bm = bm * esc + bc;
;         bm = fmaxf(bm, __shfl_xor(bm, 32));
;         if (__builtin_amdgcn_ballot_w64(bm > mrun + 8.0f) != 0ull) {
;             const float mnew = fmaxf(mrun, bm), alpha = __builtin_amdgcn_exp2f(mrun - mnew);
;             lrun *= alpha; mrun = mnew;
; #pragma unroll
;             for (int db = 0; db < 4; ++db)
; #pragma unroll
;                 for (int i = 0; i < 16; ++i) o[db][i] *= alpha;
;         }
.LBB0_719:
	s_nop 2
	v_max_f32_e32 v4, v99, v99
	v_max_f32_e32 v5, v83, v83
	v_max_f32_e32 v4, v5, v4
	v_max_f32_e32 v5, v100, v100
	v_max_f32_e32 v6, v84, v84
	v_max_f32_e32 v5, v6, v5
	v_max_f32_e32 v6, v101, v101
	v_max_f32_e32 v7, v85, v85
	v_max3_f32 v4, v82, v98, v4
	v_max_f32_e32 v6, v7, v6
	v_max3_f32 v4, v4, v5, v6
	v_max_f32_e32 v5, v102, v102
	v_max_f32_e32 v6, v86, v86
	v_max_f32_e32 v5, v6, v5
	v_max_f32_e32 v6, v103, v103
	v_max_f32_e32 v7, v87, v87
	v_max_f32_e32 v6, v7, v6
	v_max3_f32 v4, v4, v5, v6
	v_max_f32_e32 v5, v104, v104
	v_max_f32_e32 v6, v88, v88
	v_max_f32_e32 v5, v6, v5
	v_max_f32_e32 v6, v105, v105
	v_max_f32_e32 v7, v89, v89
	v_max_f32_e32 v6, v7, v6
	v_max3_f32 v4, v4, v5, v6
	v_max_f32_e32 v5, v106, v106
	v_max_f32_e32 v6, v90, v90
	v_max_f32_e32 v5, v6, v5
	v_max_f32_e32 v6, v107, v107
	v_max_f32_e32 v7, v91, v91
	v_max_f32_e32 v6, v7, v6
	v_max3_f32 v4, v4, v5, v6
	v_max_f32_e32 v5, v108, v108
	v_max_f32_e32 v6, v92, v92
	v_max_f32_e32 v5, v6, v5
	v_max_f32_e32 v6, v109, v109
	v_max_f32_e32 v7, v93, v93
	v_max_f32_e32 v6, v7, v6
	v_max3_f32 v4, v4, v5, v6
	v_max_f32_e32 v5, v110, v110
	v_max_f32_e32 v6, v94, v94
	v_max_f32_e32 v5, v6, v5
	v_max_f32_e32 v6, v111, v111
	v_max_f32_e32 v7, v95, v95
	v_max_f32_e32 v6, v7, v6
	v_max3_f32 v4, v4, v5, v6
	v_max_f32_e32 v5, v112, v112
	v_max_f32_e32 v6, v96, v96
	v_max_f32_e32 v5, v6, v5
	v_max_f32_e32 v6, v113, v113
	v_max_f32_e32 v7, v97, v97
	v_max_f32_e32 v6, v7, v6
	v_max3_f32 v4, v4, v5, v6
	v_and_b32_e32 v6, 64, v223
	v_xor_b32_e32 v5, 32, v223
	v_add_u32_e32 v6, 64, v6
	v_cmp_lt_i32_e32 vcc, v5, v6
	s_waitcnt lgkmcnt(0)
	v_fma_f32 v4, s55, v4, v2
	v_cndmask_b32_e32 v5, v223, v5, vcc
	v_lshlrev_b32_e32 v5, 2, v5
	v_mov_b32_e32 v6, v4
	s_nop 1
	v_permlane32_swap_b32_e32 v4, v6
	s_waitcnt lgkmcnt(0)
	v_max_f32_e32 v6, v6, v6
	v_max_f32_e32 v4, v4, v6
	v_add_f32_e32 v6, 0x41000000, v194
	v_cmp_gt_f32_e32 vcc, v4, v6
	s_cbranch_vccz .LBB0_721
	v_max_f32_e32 v4, v4, v4
	v_max_f32_e32 v6, v194, v194
	v_max_f32_e32 v6, v6, v4
	v_sub_f32_e32 v4, v194, v6
	v_exp_f32_e32 v4, v4
	v_mov_b32_e32 v194, v6
	v_pk_mul_f32 v[80:81], v[80:81], v[4:5] op_sel_hi:[1,0]
	v_pk_mul_f32 v[78:79], v[78:79], v[4:5] op_sel_hi:[1,0]
	v_pk_mul_f32 v[76:77], v[76:77], v[4:5] op_sel_hi:[1,0]
	v_pk_mul_f32 v[74:75], v[74:75], v[4:5] op_sel_hi:[1,0]
	v_pk_mul_f32 v[72:73], v[72:73], v[4:5] op_sel_hi:[1,0]
	v_pk_mul_f32 v[70:71], v[70:71], v[4:5] op_sel_hi:[1,0]
	v_pk_mul_f32 v[68:69], v[68:69], v[4:5] op_sel_hi:[1,0]
	v_pk_mul_f32 v[66:67], v[66:67], v[4:5] op_sel_hi:[1,0]
	v_pk_mul_f32 v[64:65], v[64:65], v[4:5] op_sel_hi:[1,0]
	v_pk_mul_f32 v[62:63], v[62:63], v[4:5] op_sel_hi:[1,0]
	v_pk_mul_f32 v[60:61], v[60:61], v[4:5] op_sel_hi:[1,0]
	v_pk_mul_f32 v[58:59], v[58:59], v[4:5] op_sel_hi:[1,0]
	v_pk_mul_f32 v[56:57], v[56:57], v[4:5] op_sel_hi:[1,0]
	v_pk_mul_f32 v[54:55], v[54:55], v[4:5] op_sel_hi:[1,0]
	v_pk_mul_f32 v[52:53], v[52:53], v[4:5] op_sel_hi:[1,0]
	v_pk_mul_f32 v[50:51], v[50:51], v[4:5] op_sel_hi:[1,0]
	v_pk_mul_f32 v[48:49], v[48:49], v[4:5] op_sel_hi:[1,0]
	v_pk_mul_f32 v[46:47], v[46:47], v[4:5] op_sel_hi:[1,0]
	v_pk_mul_f32 v[44:45], v[44:45], v[4:5] op_sel_hi:[1,0]
	v_pk_mul_f32 v[42:43], v[42:43], v[4:5] op_sel_hi:[1,0]
	v_pk_mul_f32 v[40:41], v[40:41], v[4:5] op_sel_hi:[1,0]
	v_pk_mul_f32 v[38:39], v[38:39], v[4:5] op_sel_hi:[1,0]
	v_pk_mul_f32 v[36:37], v[36:37], v[4:5] op_sel_hi:[1,0]
	v_pk_mul_f32 v[34:35], v[34:35], v[4:5] op_sel_hi:[1,0]
	v_pk_mul_f32 v[32:33], v[32:33], v[4:5] op_sel_hi:[1,0]
	v_pk_mul_f32 v[30:31], v[30:31], v[4:5] op_sel_hi:[1,0]
	v_pk_mul_f32 v[28:29], v[28:29], v[4:5] op_sel_hi:[1,0]
	v_pk_mul_f32 v[26:27], v[26:27], v[4:5] op_sel_hi:[1,0]
	v_pk_mul_f32 v[24:25], v[24:25], v[4:5] op_sel_hi:[1,0]
	v_pk_mul_f32 v[22:23], v[22:23], v[4:5] op_sel_hi:[1,0]
	v_pk_mul_f32 v[20:21], v[20:21], v[4:5] op_sel_hi:[1,0]
	v_pk_mul_f32 v[18:19], v[18:19], v[4:5] op_sel_hi:[1,0]
	v_mul_f32_e32 v192, v192, v4

; template <int MODE, class Src>
; DI void attn_item(LAS unsigned char* lds, const Src& src, const bf16_t* Qp  , bf16_t* Op  , int nband, int jj0, float sink_l2, const LAS float* tbl, int qbase, int tid) {
;     ...
;         float bm = fmaxf(s[0][0], s[1][0]);
; #pragma unroll
;         for (int i = 1; i < 16; ++i) bm = fmaxf(bm, fmaxf(s[0][i], s[1][i]));
;         bm = bm * esc + bc;
;         bm = fmaxf(bm, __shfl_xor(bm, 32));
;         if (__builtin_amdgcn_ballot_w64(bm > mrun + 8.0f) != 0ull) {
;             const float mnew = fmaxf(mrun, bm), alpha = __builtin_amdgcn_exp2f(mrun - mnew);
;             lrun *= alpha; mrun = mnew;
; #pragma unroll
;             for (int db = 0; db < 4; ++db)
; #pragma unroll
;                 for (int i = 0; i < 16; ++i) o[db][i] *= alpha;
;         }
.LBB0_764:
	s_nop 10
	v_max_f32_e32 v2, v99, v99
	v_max_f32_e32 v4, v83, v83
	v_max_f32_e32 v2, v4, v2
	v_max_f32_e32 v4, v100, v100
	v_max_f32_e32 v5, v84, v84
	v_max_f32_e32 v4, v5, v4
	v_max_f32_e32 v5, v101, v101
	v_max_f32_e32 v6, v85, v85
	v_max3_f32 v2, v82, v98, v2
	v_max_f32_e32 v5, v6, v5
	v_max3_f32 v2, v2, v4, v5
	v_max_f32_e32 v4, v102, v102
	v_max_f32_e32 v5, v86, v86
	v_max_f32_e32 v4, v5, v4
	v_max_f32_e32 v5, v103, v103
	v_max_f32_e32 v6, v87, v87
	v_max_f32_e32 v5, v6, v5
	v_max3_f32 v2, v2, v4, v5
	v_max_f32_e32 v4, v104, v104
	v_max_f32_e32 v5, v88, v88
	v_max_f32_e32 v4, v5, v4
	v_max_f32_e32 v5, v105, v105
	v_max_f32_e32 v6, v89, v89
	v_max_f32_e32 v5, v6, v5
	v_max3_f32 v2, v2, v4, v5
	v_max_f32_e32 v4, v106, v106
	v_max_f32_e32 v5, v90, v90
	v_max_f32_e32 v4, v5, v4
	v_max_f32_e32 v5, v107, v107
	v_max_f32_e32 v6, v91, v91
	v_max_f32_e32 v5, v6, v5
	v_max3_f32 v2, v2, v4, v5
	v_max_f32_e32 v4, v108, v108
	v_max_f32_e32 v5, v92, v92
	v_max_f32_e32 v4, v5, v4
	v_max_f32_e32 v5, v109, v109
	v_max_f32_e32 v6, v93, v93
	v_max_f32_e32 v5, v6, v5
	v_max3_f32 v2, v2, v4, v5
	v_max_f32_e32 v4, v110, v110
	v_max_f32_e32 v5, v94, v94
	v_max_f32_e32 v4, v5, v4
	v_max_f32_e32 v5, v111, v111
	v_max_f32_e32 v6, v95, v95
	v_max_f32_e32 v5, v6, v5
	v_max3_f32 v2, v2, v4, v5
	v_max_f32_e32 v4, v112, v112
	v_max_f32_e32 v5, v96, v96
	v_max_f32_e32 v4, v5, v4
	v_max_f32_e32 v5, v113, v113
	v_max_f32_e32 v6, v97, v97
	v_max_f32_e32 v5, v6, v5
	v_max3_f32 v2, v2, v4, v5
	v_and_b32_e32 v5, 64, v223
	v_fma_f32 v4, v2, s30, 0
	v_xor_b32_e32 v2, 32, v223
	v_add_u32_e32 v5, 64, v5
	v_cmp_lt_i32_e32 vcc, v2, v5
	s_nop 1
	v_cndmask_b32_e32 v2, v223, v2, vcc
	v_lshlrev_b32_e32 v2, 2, v2
	v_mov_b32_e32 v5, v4
	s_nop 1
	v_permlane32_swap_b32_e32 v4, v5
	s_waitcnt lgkmcnt(0)
	v_max_f32_e32 v5, v5, v5
	v_max_f32_e32 v4, v4, v5
	v_add_f32_e32 v5, 0x41000000, v157
	v_cmp_gt_f32_e32 vcc, v4, v5
	s_cbranch_vccz .LBB0_766
	v_max_f32_e32 v4, v4, v4
	v_max_f32_e32 v5, v157, v157
	v_max_f32_e32 v5, v5, v4
	v_sub_f32_e32 v4, v157, v5
	v_exp_f32_e32 v4, v4
	v_mov_b32_e32 v157, v5
	v_pk_mul_f32 v[80:81], v[80:81], v[4:5] op_sel_hi:[1,0]
	v_pk_mul_f32 v[78:79], v[78:79], v[4:5] op_sel_hi:[1,0]
	v_pk_mul_f32 v[76:77], v[76:77], v[4:5] op_sel_hi:[1,0]
	v_pk_mul_f32 v[74:75], v[74:75], v[4:5] op_sel_hi:[1,0]
	v_pk_mul_f32 v[72:73], v[72:73], v[4:5] op_sel_hi:[1,0]
	v_pk_mul_f32 v[70:71], v[70:71], v[4:5] op_sel_hi:[1,0]
	v_pk_mul_f32 v[68:69], v[68:69], v[4:5] op_sel_hi:[1,0]
	v_pk_mul_f32 v[66:67], v[66:67], v[4:5] op_sel_hi:[1,0]
	v_pk_mul_f32 v[64:65], v[64:65], v[4:5] op_sel_hi:[1,0]
	v_pk_mul_f32 v[62:63], v[62:63], v[4:5] op_sel_hi:[1,0]
	v_pk_mul_f32 v[60:61], v[60:61], v[4:5] op_sel_hi:[1,0]
	v_pk_mul_f32 v[58:59], v[58:59], v[4:5] op_sel_hi:[1,0]
	v_pk_mul_f32 v[56:57], v[56:57], v[4:5] op_sel_hi:[1,0]
	v_pk_mul_f32 v[54:55], v[54:55], v[4:5] op_sel_hi:[1,0]
	v_pk_mul_f32 v[52:53], v[52:53], v[4:5] op_sel_hi:[1,0]
	v_pk_mul_f32 v[50:51], v[50:51], v[4:5] op_sel_hi:[1,0]
	v_pk_mul_f32 v[48:49], v[48:49], v[4:5] op_sel_hi:[1,0]
	v_pk_mul_f32 v[46:47], v[46:47], v[4:5] op_sel_hi:[1,0]
	v_pk_mul_f32 v[44:45], v[44:45], v[4:5] op_sel_hi:[1,0]
	v_pk_mul_f32 v[42:43], v[42:43], v[4:5] op_sel_hi:[1,0]
	v_pk_mul_f32 v[40:41], v[40:41], v[4:5] op_sel_hi:[1,0]
	v_pk_mul_f32 v[38:39], v[38:39], v[4:5] op_sel_hi:[1,0]
	v_pk_mul_f32 v[36:37], v[36:37], v[4:5] op_sel_hi:[1,0]
	v_pk_mul_f32 v[34:35], v[34:35], v[4:5] op_sel_hi:[1,0]
	v_pk_mul_f32 v[32:33], v[32:33], v[4:5] op_sel_hi:[1,0]
	v_pk_mul_f32 v[30:31], v[30:31], v[4:5] op_sel_hi:[1,0]
	v_pk_mul_f32 v[28:29], v[28:29], v[4:5] op_sel_hi:[1,0]
	v_pk_mul_f32 v[26:27], v[26:27], v[4:5] op_sel_hi:[1,0]
	v_pk_mul_f32 v[24:25], v[24:25], v[4:5] op_sel_hi:[1,0]
	v_pk_mul_f32 v[22:23], v[22:23], v[4:5] op_sel_hi:[1,0]
	v_pk_mul_f32 v[20:21], v[20:21], v[4:5] op_sel_hi:[1,0]
	v_pk_mul_f32 v[18:19], v[18:19], v[4:5] op_sel_hi:[1,0]
	v_mul_f32_e32 v151, v151, v4
